# attention block epilogue rewritten: DPP quad_perm lane swap + batched exec-masked stores instead of 64 serialized ds_bpermute/store round trips
# baseline (speedup 1.0000x reference)
.LBB0_576:
	s_and_saveexec_b64 s[4:5], s[0:1]
	ds_write_b32 v206, v211
	s_or_b64 exec, exec, s[4:5]
	s_waitcnt lgkmcnt(0)
	ds_read_b128 v[78:81], v207
	ds_read_b128 v[74:77], v207 offset:32
	ds_read_b128 v[70:73], v207 offset:64
	ds_read_b128 v[66:69], v207 offset:96
	s_add_u32 s4, s74, s46
	s_addc_u32 s5, s75, s47
	v_mov_b32_e32 v181, v1
	v_lshl_add_u64 v[216:217], s[4:5], 0, v[180:181]
	v_lshl_add_u64 v[216:217], v[216:217], 0, v[174:175]
	s_waitcnt lgkmcnt(0)
	v_rcp_f32_e32 v78, v78
	v_rcp_f32_e32 v79, v79
	v_rcp_f32_e32 v80, v80
	v_rcp_f32_e32 v81, v81
	v_rcp_f32_e32 v74, v74
	v_rcp_f32_e32 v75, v75
	v_rcp_f32_e32 v76, v76
	v_rcp_f32_e32 v77, v77
	v_rcp_f32_e32 v70, v70
	v_rcp_f32_e32 v71, v71
	v_rcp_f32_e32 v72, v72
	v_rcp_f32_e32 v73, v73
	v_rcp_f32_e32 v66, v66
	v_rcp_f32_e32 v67, v67
	v_rcp_f32_e32 v68, v68
	v_rcp_f32_e32 v69, v69
	s_nop 0
	v_mul_f32_e32 v50, v50, v78
	v_mul_f32_e32 v34, v34, v78
	v_mul_f32_e32 v18, v18, v78
	v_mul_f32_e32 v2, v2, v78
	v_mul_f32_e32 v51, v51, v79
	v_mul_f32_e32 v35, v35, v79
	v_mul_f32_e32 v19, v19, v79
	v_mul_f32_e32 v3, v3, v79
	v_mul_f32_e32 v52, v52, v80
	v_mul_f32_e32 v36, v36, v80
	v_mul_f32_e32 v20, v20, v80
	v_mul_f32_e32 v4, v4, v80
	v_mul_f32_e32 v53, v53, v81
	v_mul_f32_e32 v37, v37, v81
	v_mul_f32_e32 v21, v21, v81
	v_mul_f32_e32 v5, v5, v81
	v_mul_f32_e32 v54, v54, v74
	v_mul_f32_e32 v38, v38, v74
	v_mul_f32_e32 v22, v22, v74
	v_mul_f32_e32 v6, v6, v74
	v_mul_f32_e32 v55, v55, v75
	v_mul_f32_e32 v39, v39, v75
	v_mul_f32_e32 v23, v23, v75
	v_mul_f32_e32 v7, v7, v75
	v_mul_f32_e32 v56, v56, v76
	v_mul_f32_e32 v40, v40, v76
	v_mul_f32_e32 v24, v24, v76
	v_mul_f32_e32 v8, v8, v76
	v_mul_f32_e32 v57, v57, v77
	v_mul_f32_e32 v41, v41, v77
	v_mul_f32_e32 v25, v25, v77
	v_mul_f32_e32 v9, v9, v77
	v_mul_f32_e32 v58, v58, v70
	v_mul_f32_e32 v42, v42, v70
	v_mul_f32_e32 v26, v26, v70
	v_mul_f32_e32 v10, v10, v70
	v_mul_f32_e32 v59, v59, v71
	v_mul_f32_e32 v43, v43, v71
	v_mul_f32_e32 v27, v27, v71
	v_mul_f32_e32 v11, v11, v71
	v_mul_f32_e32 v60, v60, v72
	v_mul_f32_e32 v44, v44, v72
	v_mul_f32_e32 v28, v28, v72
	v_mul_f32_e32 v12, v12, v72
	v_mul_f32_e32 v61, v61, v73
	v_mul_f32_e32 v45, v45, v73
	v_mul_f32_e32 v29, v29, v73
	v_mul_f32_e32 v13, v13, v73
	v_mul_f32_e32 v62, v62, v66
	v_mul_f32_e32 v46, v46, v66
	v_mul_f32_e32 v30, v30, v66
	v_mul_f32_e32 v14, v14, v66
	v_mul_f32_e32 v63, v63, v67
	v_mul_f32_e32 v47, v47, v67
	v_mul_f32_e32 v31, v31, v67
	v_mul_f32_e32 v15, v15, v67
	v_mul_f32_e32 v64, v64, v68
	v_mul_f32_e32 v48, v48, v68
	v_mul_f32_e32 v32, v32, v68
	v_mul_f32_e32 v16, v16, v68
	v_mul_f32_e32 v65, v65, v69
	v_mul_f32_e32 v49, v49, v69
	v_mul_f32_e32 v33, v33, v69
	v_mul_f32_e32 v17, v17, v69
	v_add_co_u32_e32 v218, vcc, 0x1000, v216
	s_nop 1
	v_addc_co_u32_e32 v219, vcc, 0, v217, vcc
	v_mov_b32_dpp v82, v50 quad_perm:[1,0,3,2] row_mask:0xf bank_mask:0xf
	v_mov_b32_dpp v83, v34 quad_perm:[1,0,3,2] row_mask:0xf bank_mask:0xf
	v_mov_b32_dpp v84, v18 quad_perm:[1,0,3,2] row_mask:0xf bank_mask:0xf
	v_mov_b32_dpp v85, v2 quad_perm:[1,0,3,2] row_mask:0xf bank_mask:0xf
	v_mov_b32_dpp v86, v51 quad_perm:[1,0,3,2] row_mask:0xf bank_mask:0xf
	v_mov_b32_dpp v87, v35 quad_perm:[1,0,3,2] row_mask:0xf bank_mask:0xf
	v_mov_b32_dpp v88, v19 quad_perm:[1,0,3,2] row_mask:0xf bank_mask:0xf
	v_mov_b32_dpp v89, v3 quad_perm:[1,0,3,2] row_mask:0xf bank_mask:0xf
	v_mov_b32_dpp v90, v52 quad_perm:[1,0,3,2] row_mask:0xf bank_mask:0xf
	v_mov_b32_dpp v91, v36 quad_perm:[1,0,3,2] row_mask:0xf bank_mask:0xf
	v_mov_b32_dpp v92, v20 quad_perm:[1,0,3,2] row_mask:0xf bank_mask:0xf
	v_mov_b32_dpp v93, v4 quad_perm:[1,0,3,2] row_mask:0xf bank_mask:0xf
	v_mov_b32_dpp v94, v53 quad_perm:[1,0,3,2] row_mask:0xf bank_mask:0xf
	v_mov_b32_dpp v95, v37 quad_perm:[1,0,3,2] row_mask:0xf bank_mask:0xf
	v_mov_b32_dpp v96, v21 quad_perm:[1,0,3,2] row_mask:0xf bank_mask:0xf
	v_mov_b32_dpp v97, v5 quad_perm:[1,0,3,2] row_mask:0xf bank_mask:0xf
	v_cvt_pk_bf16_f32 v82, v50, v82
	v_cvt_pk_bf16_f32 v83, v34, v83
	v_cvt_pk_bf16_f32 v84, v18, v84
	v_cvt_pk_bf16_f32 v85, v2, v85
	v_cvt_pk_bf16_f32 v86, v51, v86
	v_cvt_pk_bf16_f32 v87, v35, v87
	v_cvt_pk_bf16_f32 v88, v19, v88
	v_cvt_pk_bf16_f32 v89, v3, v89
	v_cvt_pk_bf16_f32 v90, v52, v90
	v_cvt_pk_bf16_f32 v91, v36, v91
	v_cvt_pk_bf16_f32 v92, v20, v92
	v_cvt_pk_bf16_f32 v93, v4, v93
	v_cvt_pk_bf16_f32 v94, v53, v94
	v_cvt_pk_bf16_f32 v95, v37, v95
	v_cvt_pk_bf16_f32 v96, v21, v96
	v_cvt_pk_bf16_f32 v97, v5, v97
	s_and_saveexec_b64 s[4:5], s[6:7]
	global_store_dword v[216:217], v82, off
	global_store_dword v[216:217], v83, off offset:64
	global_store_dword v[216:217], v84, off offset:128
	global_store_dword v[216:217], v85, off offset:192
	global_store_dword v[216:217], v86, off offset:2048
	global_store_dword v[216:217], v87, off offset:2112
	global_store_dword v[216:217], v88, off offset:2176
	global_store_dword v[216:217], v89, off offset:2240
	global_store_dword v[218:219], v90, off
	global_store_dword v[218:219], v91, off offset:64
	global_store_dword v[218:219], v92, off offset:128
	global_store_dword v[218:219], v93, off offset:192
	global_store_dword v[218:219], v94, off offset:2048
	global_store_dword v[218:219], v95, off offset:2112
	global_store_dword v[218:219], v96, off offset:2176
	global_store_dword v[218:219], v97, off offset:2240
	s_or_b64 exec, exec, s[4:5]
	v_add_co_u32_e32 v216, vcc, 0x4000, v216
	s_nop 1
	v_addc_co_u32_e32 v217, vcc, 0, v217, vcc
	v_add_co_u32_e32 v218, vcc, 0x1000, v216
	s_nop 1
	v_addc_co_u32_e32 v219, vcc, 0, v217, vcc
	v_mov_b32_dpp v82, v54 quad_perm:[1,0,3,2] row_mask:0xf bank_mask:0xf
	v_mov_b32_dpp v83, v38 quad_perm:[1,0,3,2] row_mask:0xf bank_mask:0xf
	v_mov_b32_dpp v84, v22 quad_perm:[1,0,3,2] row_mask:0xf bank_mask:0xf
	v_mov_b32_dpp v85, v6 quad_perm:[1,0,3,2] row_mask:0xf bank_mask:0xf
	v_mov_b32_dpp v86, v55 quad_perm:[1,0,3,2] row_mask:0xf bank_mask:0xf
	v_mov_b32_dpp v87, v39 quad_perm:[1,0,3,2] row_mask:0xf bank_mask:0xf
	v_mov_b32_dpp v88, v23 quad_perm:[1,0,3,2] row_mask:0xf bank_mask:0xf
	v_mov_b32_dpp v89, v7 quad_perm:[1,0,3,2] row_mask:0xf bank_mask:0xf
	v_mov_b32_dpp v90, v56 quad_perm:[1,0,3,2] row_mask:0xf bank_mask:0xf
	v_mov_b32_dpp v91, v40 quad_perm:[1,0,3,2] row_mask:0xf bank_mask:0xf
	v_mov_b32_dpp v92, v24 quad_perm:[1,0,3,2] row_mask:0xf bank_mask:0xf
	v_mov_b32_dpp v93, v8 quad_perm:[1,0,3,2] row_mask:0xf bank_mask:0xf
	v_mov_b32_dpp v94, v57 quad_perm:[1,0,3,2] row_mask:0xf bank_mask:0xf
	v_mov_b32_dpp v95, v41 quad_perm:[1,0,3,2] row_mask:0xf bank_mask:0xf
	v_mov_b32_dpp v96, v25 quad_perm:[1,0,3,2] row_mask:0xf bank_mask:0xf
	v_mov_b32_dpp v97, v9 quad_perm:[1,0,3,2] row_mask:0xf bank_mask:0xf
	v_cvt_pk_bf16_f32 v82, v54, v82
	v_cvt_pk_bf16_f32 v83, v38, v83
	v_cvt_pk_bf16_f32 v84, v22, v84
	v_cvt_pk_bf16_f32 v85, v6, v85
	v_cvt_pk_bf16_f32 v86, v55, v86
	v_cvt_pk_bf16_f32 v87, v39, v87
	v_cvt_pk_bf16_f32 v88, v23, v88
	v_cvt_pk_bf16_f32 v89, v7, v89
	v_cvt_pk_bf16_f32 v90, v56, v90
	v_cvt_pk_bf16_f32 v91, v40, v91
	v_cvt_pk_bf16_f32 v92, v24, v92
	v_cvt_pk_bf16_f32 v93, v8, v93
	v_cvt_pk_bf16_f32 v94, v57, v94
	v_cvt_pk_bf16_f32 v95, v41, v95
	v_cvt_pk_bf16_f32 v96, v25, v96
	v_cvt_pk_bf16_f32 v97, v9, v97
	s_and_saveexec_b64 s[4:5], s[6:7]
	global_store_dword v[216:217], v82, off
	global_store_dword v[216:217], v83, off offset:64
	global_store_dword v[216:217], v84, off offset:128
	global_store_dword v[216:217], v85, off offset:192
	global_store_dword v[216:217], v86, off offset:2048
	global_store_dword v[216:217], v87, off offset:2112
	global_store_dword v[216:217], v88, off offset:2176
	global_store_dword v[216:217], v89, off offset:2240
	global_store_dword v[218:219], v90, off
	global_store_dword v[218:219], v91, off offset:64
	global_store_dword v[218:219], v92, off offset:128
	global_store_dword v[218:219], v93, off offset:192
	global_store_dword v[218:219], v94, off offset:2048
	global_store_dword v[218:219], v95, off offset:2112
	global_store_dword v[218:219], v96, off offset:2176
	global_store_dword v[218:219], v97, off offset:2240
	s_or_b64 exec, exec, s[4:5]
	v_add_co_u32_e32 v216, vcc, 0x4000, v216
	s_nop 1
	v_addc_co_u32_e32 v217, vcc, 0, v217, vcc
	v_add_co_u32_e32 v218, vcc, 0x1000, v216
	s_nop 1
	v_addc_co_u32_e32 v219, vcc, 0, v217, vcc
	v_mov_b32_dpp v82, v58 quad_perm:[1,0,3,2] row_mask:0xf bank_mask:0xf
	v_mov_b32_dpp v83, v42 quad_perm:[1,0,3,2] row_mask:0xf bank_mask:0xf
	v_mov_b32_dpp v84, v26 quad_perm:[1,0,3,2] row_mask:0xf bank_mask:0xf
	v_mov_b32_dpp v85, v10 quad_perm:[1,0,3,2] row_mask:0xf bank_mask:0xf
	v_mov_b32_dpp v86, v59 quad_perm:[1,0,3,2] row_mask:0xf bank_mask:0xf
	v_mov_b32_dpp v87, v43 quad_perm:[1,0,3,2] row_mask:0xf bank_mask:0xf
	v_mov_b32_dpp v88, v27 quad_perm:[1,0,3,2] row_mask:0xf bank_mask:0xf
	v_mov_b32_dpp v89, v11 quad_perm:[1,0,3,2] row_mask:0xf bank_mask:0xf
	v_mov_b32_dpp v90, v60 quad_perm:[1,0,3,2] row_mask:0xf bank_mask:0xf
	v_mov_b32_dpp v91, v44 quad_perm:[1,0,3,2] row_mask:0xf bank_mask:0xf
	v_mov_b32_dpp v92, v28 quad_perm:[1,0,3,2] row_mask:0xf bank_mask:0xf
	v_mov_b32_dpp v93, v12 quad_perm:[1,0,3,2] row_mask:0xf bank_mask:0xf
	v_mov_b32_dpp v94, v61 quad_perm:[1,0,3,2] row_mask:0xf bank_mask:0xf
	v_mov_b32_dpp v95, v45 quad_perm:[1,0,3,2] row_mask:0xf bank_mask:0xf
	v_mov_b32_dpp v96, v29 quad_perm:[1,0,3,2] row_mask:0xf bank_mask:0xf
	v_mov_b32_dpp v97, v13 quad_perm:[1,0,3,2] row_mask:0xf bank_mask:0xf
	v_cvt_pk_bf16_f32 v82, v58, v82
	v_cvt_pk_bf16_f32 v83, v42, v83
	v_cvt_pk_bf16_f32 v84, v26, v84
	v_cvt_pk_bf16_f32 v85, v10, v85
	v_cvt_pk_bf16_f32 v86, v59, v86
	v_cvt_pk_bf16_f32 v87, v43, v87
	v_cvt_pk_bf16_f32 v88, v27, v88
	v_cvt_pk_bf16_f32 v89, v11, v89
	v_cvt_pk_bf16_f32 v90, v60, v90
	v_cvt_pk_bf16_f32 v91, v44, v91
	v_cvt_pk_bf16_f32 v92, v28, v92
	v_cvt_pk_bf16_f32 v93, v12, v93
	v_cvt_pk_bf16_f32 v94, v61, v94
	v_cvt_pk_bf16_f32 v95, v45, v95
	v_cvt_pk_bf16_f32 v96, v29, v96
	v_cvt_pk_bf16_f32 v97, v13, v97
	s_and_saveexec_b64 s[4:5], s[6:7]
	global_store_dword v[216:217], v82, off
	global_store_dword v[216:217], v83, off offset:64
	global_store_dword v[216:217], v84, off offset:128
	global_store_dword v[216:217], v85, off offset:192
	global_store_dword v[216:217], v86, off offset:2048
	global_store_dword v[216:217], v87, off offset:2112
	global_store_dword v[216:217], v88, off offset:2176
	global_store_dword v[216:217], v89, off offset:2240
	global_store_dword v[218:219], v90, off
	global_store_dword v[218:219], v91, off offset:64
	global_store_dword v[218:219], v92, off offset:128
	global_store_dword v[218:219], v93, off offset:192
	global_store_dword v[218:219], v94, off offset:2048
	global_store_dword v[218:219], v95, off offset:2112
	global_store_dword v[218:219], v96, off offset:2176
	global_store_dword v[218:219], v97, off offset:2240
	s_or_b64 exec, exec, s[4:5]
	v_add_co_u32_e32 v216, vcc, 0x4000, v216
	s_nop 1
	v_addc_co_u32_e32 v217, vcc, 0, v217, vcc
	v_add_co_u32_e32 v218, vcc, 0x1000, v216
	s_nop 1
	v_addc_co_u32_e32 v219, vcc, 0, v217, vcc
	v_mov_b32_dpp v82, v62 quad_perm:[1,0,3,2] row_mask:0xf bank_mask:0xf
	v_mov_b32_dpp v83, v46 quad_perm:[1,0,3,2] row_mask:0xf bank_mask:0xf
	v_mov_b32_dpp v84, v30 quad_perm:[1,0,3,2] row_mask:0xf bank_mask:0xf
	v_mov_b32_dpp v85, v14 quad_perm:[1,0,3,2] row_mask:0xf bank_mask:0xf
	v_mov_b32_dpp v86, v63 quad_perm:[1,0,3,2] row_mask:0xf bank_mask:0xf
	v_mov_b32_dpp v87, v47 quad_perm:[1,0,3,2] row_mask:0xf bank_mask:0xf
	v_mov_b32_dpp v88, v31 quad_perm:[1,0,3,2] row_mask:0xf bank_mask:0xf
	v_mov_b32_dpp v89, v15 quad_perm:[1,0,3,2] row_mask:0xf bank_mask:0xf
	v_mov_b32_dpp v90, v64 quad_perm:[1,0,3,2] row_mask:0xf bank_mask:0xf
	v_mov_b32_dpp v91, v48 quad_perm:[1,0,3,2] row_mask:0xf bank_mask:0xf
	v_mov_b32_dpp v92, v32 quad_perm:[1,0,3,2] row_mask:0xf bank_mask:0xf
	v_mov_b32_dpp v93, v16 quad_perm:[1,0,3,2] row_mask:0xf bank_mask:0xf
	v_mov_b32_dpp v94, v65 quad_perm:[1,0,3,2] row_mask:0xf bank_mask:0xf
	v_mov_b32_dpp v95, v49 quad_perm:[1,0,3,2] row_mask:0xf bank_mask:0xf
	v_mov_b32_dpp v96, v33 quad_perm:[1,0,3,2] row_mask:0xf bank_mask:0xf
	v_mov_b32_dpp v97, v17 quad_perm:[1,0,3,2] row_mask:0xf bank_mask:0xf
	v_cvt_pk_bf16_f32 v82, v62, v82
	v_cvt_pk_bf16_f32 v83, v46, v83
	v_cvt_pk_bf16_f32 v84, v30, v84
	v_cvt_pk_bf16_f32 v85, v14, v85
	v_cvt_pk_bf16_f32 v86, v63, v86
	v_cvt_pk_bf16_f32 v87, v47, v87
	v_cvt_pk_bf16_f32 v88, v31, v88
	v_cvt_pk_bf16_f32 v89, v15, v89
	v_cvt_pk_bf16_f32 v90, v64, v90
	v_cvt_pk_bf16_f32 v91, v48, v91
	v_cvt_pk_bf16_f32 v92, v32, v92
	v_cvt_pk_bf16_f32 v93, v16, v93
	v_cvt_pk_bf16_f32 v94, v65, v94
	v_cvt_pk_bf16_f32 v95, v49, v95
	v_cvt_pk_bf16_f32 v96, v33, v96
	v_cvt_pk_bf16_f32 v97, v17, v97
	s_and_saveexec_b64 s[4:5], s[6:7]
	global_store_dword v[216:217], v82, off
	global_store_dword v[216:217], v83, off offset:64
	global_store_dword v[216:217], v84, off offset:128
	global_store_dword v[216:217], v85, off offset:192
	global_store_dword v[216:217], v86, off offset:2048
	global_store_dword v[216:217], v87, off offset:2112
	global_store_dword v[216:217], v88, off offset:2176
	global_store_dword v[216:217], v89, off offset:2240
	global_store_dword v[218:219], v90, off
	global_store_dword v[218:219], v91, off offset:64
	global_store_dword v[218:219], v92, off offset:128
	global_store_dword v[218:219], v93, off offset:192
	global_store_dword v[218:219], v94, off offset:2048
	global_store_dword v[218:219], v95, off offset:2112
	global_store_dword v[218:219], v96, off offset:2176
	global_store_dword v[218:219], v97, off offset:2240
	s_or_b64 exec, exec, s[4:5]
